# P3: batch sample-stream cache loads; sample waves hand 2 prompt tasks to waves 0/1; branch-free 1-round-trip y_s epilogue for full prompt groups
# speedup vs baseline: 1.0221x; 1.0221x over previous
; __global__ __launch_bounds__(512, 2) void fwd_mega(Args a0_) {
;     ...
;             const int nfull = (NPT / ngw) * ngw;
;             for (int task = gw; task < nfull; task += ngw) attn_task<false>(a, vl, lane, task);
;             if (wave == 0) { for (int task = nfull + blockIdx.x; task < NPT; task += G) attn_task<false>(a, vl, lane, task); }
;             if (wave == 4) { for (int task = NPT + ((blockIdx.x + G / 2) % G); task < NTASK; task += G) attn_task<true>(a, vl, lane, task); }
.LBB0_55:
	s_or_b64 exec, exec, s[0:1]
	s_add_i32 s21, s21, s97
	v_readlane_b32 s1, v254, 43
	v_readlane_b32 s0, v255, 15
	s_cmp_lg_u32 s0, 4
	v_readlane_b32 s0, v254, 29
	s_cbranch_scc1 .Lsb_lim
	s_cmpk_lg_i32 s84, 0x100
	s_cbranch_scc1 .Lsb_lim
	v_readlane_b32 s0, v254, 35
	s_cmp_eq_u32 s0, 0
	v_readlane_b32 s0, v254, 29
	s_cbranch_scc1 .Lsb_lim
	s_lshl_b32 s0, s97, 1
.Lsb_lim:
	s_cmp_ge_i32 s21, s0
	v_add_u32_e32 v209, s1, v209
	v_add_u32_e32 v210, s1, v210
	s_cbranch_scc1 .LBB0_189

; __device__ __forceinline__ unsigned pk2(float lo, float hi) { unsigned r; asm("v_cvt_pk_bf16_f32 %0, %1, %2" : "=v"(r) : "v"(lo), "v"(hi)); return r; }
; template <bool sample> __device__ __forceinline__ void attn_task(const Args& a, LAS unsigned char* vl, int lane, int task) {
;     ...
;     int lane2 = lane; asm volatile("" : "+v"(lane2));
;     const int r2 = lane2 & 31, h2 = lane2 >> 5;
;     const size_t obase = (size_t)(row0 + t0 + 4 * h2) * DM + hd * HD + r2, ybase = (size_t)(row0 + t0 + 4 * h2) * LDY + hd * HD + r2;
; #pragma unroll
;     for (int db = 0; db < 4; ++db) {
;         unsigned zv[16];
; #pragma unroll
;         for (int i = 0; i < 16; ++i) zv[i] = SZ_[obase + (size_t)(8 * (i >> 2) + (i & 3)) * DM + 32 * db];
; #pragma unroll
;         for (int i = 0; i < 16; ++i) asm volatile("" : "+v"(zv[i]));
; #pragma unroll
;         for (int i = 0; i < 16; ++i) {
;             const int q = 8 * (i >> 2) + 4 * h2 + (i & 3);
;             const bool ok = sample ? (q < NSQ) : (t0 + q < TP);
;             const float y = __uint_as_float(zv[i] << 16) * O[db][i];
;             if (ok) YS[ybase + (size_t)(8 * (i >> 2) + (i & 3)) * LDY + 32 * db] = (bf16_t)(pk2(y, y) & 0xffffu);
;         }
;     }
.LBB0_61:
	s_add_i32 s0, s22, 32
	s_cmpk_gt_i32 s0, 0x2010
	s_cbranch_scc1 .Lsb_ep_orig
	v_and_b32_e32 v69, 31, v186
	v_lshrrev_b32_e32 v70, 5, v186
	v_lshlrev_b32_e32 v69, 1, v69
	v_lshl_add_u32 v71, v70, 13, v69
	v_lshl_add_u32 v70, v70, 14, v69
	v_readlane_b32 s38, v252, 12
	v_readlane_b32 s39, v252, 13
	v_readlane_b32 s40, v252, 14
	v_readlane_b32 s41, v252, 15
	s_lshl_b64 s[0:1], s[68:69], 1
	s_add_u32 s38, s38, s0
	s_addc_u32 s39, s39, s1
	s_add_u32 s40, s40, s0
	s_addc_u32 s41, s41, s1
	s_lshl_b32 s0, s23, 11
	s_add_u32 s42, s38, s0
	s_addc_u32 s43, s39, 0
	s_lshl_b32 s0, s23, 12
	s_add_u32 s44, s40, s0
	s_addc_u32 s45, s41, 0
	s_nop 0
	global_load_ushort v80, v71, s[42:43]
	global_load_ushort v96, v71, s[42:43] offset:64
	global_load_ushort v112, v71, s[42:43] offset:128
	global_load_ushort v128, v71, s[42:43] offset:192
	global_load_ushort v81, v71, s[42:43] offset:2048
	global_load_ushort v97, v71, s[42:43] offset:2112
	global_load_ushort v113, v71, s[42:43] offset:2176
	global_load_ushort v129, v71, s[42:43] offset:2240
	s_add_u32 s42, s42, 0x1000
	s_addc_u32 s43, s43, 0
	s_nop 0
	global_load_ushort v82, v71, s[42:43]
	global_load_ushort v98, v71, s[42:43] offset:64
	global_load_ushort v114, v71, s[42:43] offset:128
	global_load_ushort v130, v71, s[42:43] offset:192
	global_load_ushort v83, v71, s[42:43] offset:2048
	global_load_ushort v99, v71, s[42:43] offset:2112
	global_load_ushort v115, v71, s[42:43] offset:2176
	global_load_ushort v131, v71, s[42:43] offset:2240
	s_add_u32 s42, s42, 0x3000
	s_addc_u32 s43, s43, 0
	s_nop 0
	global_load_ushort v84, v71, s[42:43]
	global_load_ushort v100, v71, s[42:43] offset:64
	global_load_ushort v116, v71, s[42:43] offset:128
	global_load_ushort v132, v71, s[42:43] offset:192
	global_load_ushort v85, v71, s[42:43] offset:2048
	global_load_ushort v101, v71, s[42:43] offset:2112
	global_load_ushort v117, v71, s[42:43] offset:2176
	global_load_ushort v133, v71, s[42:43] offset:2240
	s_add_u32 s42, s42, 0x1000
	s_addc_u32 s43, s43, 0
	s_nop 0
	global_load_ushort v86, v71, s[42:43]
	global_load_ushort v102, v71, s[42:43] offset:64
	global_load_ushort v118, v71, s[42:43] offset:128
	global_load_ushort v134, v71, s[42:43] offset:192
	global_load_ushort v87, v71, s[42:43] offset:2048
	global_load_ushort v103, v71, s[42:43] offset:2112
	global_load_ushort v119, v71, s[42:43] offset:2176
	global_load_ushort v135, v71, s[42:43] offset:2240
	s_add_u32 s42, s42, 0x3000
	s_addc_u32 s43, s43, 0
	s_nop 0
	global_load_ushort v88, v71, s[42:43]
	global_load_ushort v104, v71, s[42:43] offset:64
	global_load_ushort v120, v71, s[42:43] offset:128
	global_load_ushort v136, v71, s[42:43] offset:192
	global_load_ushort v89, v71, s[42:43] offset:2048
	global_load_ushort v105, v71, s[42:43] offset:2112
	global_load_ushort v121, v71, s[42:43] offset:2176
	global_load_ushort v137, v71, s[42:43] offset:2240
	s_add_u32 s42, s42, 0x1000
	s_addc_u32 s43, s43, 0
	s_nop 0
	global_load_ushort v90, v71, s[42:43]
	global_load_ushort v106, v71, s[42:43] offset:64
	global_load_ushort v122, v71, s[42:43] offset:128
	global_load_ushort v138, v71, s[42:43] offset:192
	global_load_ushort v91, v71, s[42:43] offset:2048
	global_load_ushort v107, v71, s[42:43] offset:2112
	global_load_ushort v123, v71, s[42:43] offset:2176
	global_load_ushort v139, v71, s[42:43] offset:2240
	s_add_u32 s42, s42, 0x3000
	s_addc_u32 s43, s43, 0
	s_nop 0
	global_load_ushort v92, v71, s[42:43]
	global_load_ushort v108, v71, s[42:43] offset:64
	global_load_ushort v124, v71, s[42:43] offset:128
	global_load_ushort v140, v71, s[42:43] offset:192
	global_load_ushort v93, v71, s[42:43] offset:2048
	global_load_ushort v109, v71, s[42:43] offset:2112
	global_load_ushort v125, v71, s[42:43] offset:2176
	global_load_ushort v141, v71, s[42:43] offset:2240
	s_add_u32 s42, s42, 0x1000
	s_addc_u32 s43, s43, 0
	s_nop 0
	global_load_ushort v94, v71, s[42:43]
	global_load_ushort v110, v71, s[42:43] offset:64
	global_load_ushort v126, v71, s[42:43] offset:128
	global_load_ushort v142, v71, s[42:43] offset:192
	global_load_ushort v95, v71, s[42:43] offset:2048
	global_load_ushort v111, v71, s[42:43] offset:2112
	global_load_ushort v127, v71, s[42:43] offset:2176
	global_load_ushort v143, v71, s[42:43] offset:2240
	s_waitcnt vmcnt(60)
	v_lshlrev_b32_e32 v80, 16, v80
	v_lshlrev_b32_e32 v96, 16, v96
	v_lshlrev_b32_e32 v112, 16, v112
	v_lshlrev_b32_e32 v128, 16, v128
	v_mul_f32_e32 v80, v48, v80
	v_mul_f32_e32 v96, v32, v96
	v_mul_f32_e32 v112, v16, v112
	v_mul_f32_e32 v128, v0, v128
	v_cvt_pk_bf16_f32 v80, v80, v96
	v_cvt_pk_bf16_f32 v112, v112, v128
	global_store_short v70, v80, s[44:45]
	global_store_short_d16_hi v70, v80, s[44:45] offset:64
	global_store_short v70, v112, s[44:45] offset:128
	global_store_short_d16_hi v70, v112, s[44:45] offset:192
	s_add_u32 s44, s44, 0x1000
	s_addc_u32 s45, s45, 0
	s_waitcnt vmcnt(60)
	v_lshlrev_b32_e32 v81, 16, v81
	v_lshlrev_b32_e32 v97, 16, v97
	v_lshlrev_b32_e32 v113, 16, v113
	v_lshlrev_b32_e32 v129, 16, v129
	v_mul_f32_e32 v81, v49, v81
	v_mul_f32_e32 v97, v33, v97
	v_mul_f32_e32 v113, v17, v113
	v_mul_f32_e32 v129, v1, v129
	v_cvt_pk_bf16_f32 v81, v81, v97
	v_cvt_pk_bf16_f32 v113, v113, v129
	global_store_short v70, v81, s[44:45]
	global_store_short_d16_hi v70, v81, s[44:45] offset:64
	global_store_short v70, v113, s[44:45] offset:128
	global_store_short_d16_hi v70, v113, s[44:45] offset:192
	s_add_u32 s44, s44, 0x1000
	s_addc_u32 s45, s45, 0
	s_waitcnt vmcnt(60)
; __device__ __forceinline__ unsigned pk2(float lo, float hi) { unsigned r; asm("v_cvt_pk_bf16_f32 %0, %1, %2" : "=v"(r) : "v"(lo), "v"(hi)); return r; }
; template <bool sample> __device__ __forceinline__ void attn_task(const Args& a, LAS unsigned char* vl, int lane, int task) {
;     ...
;     int lane2 = lane; asm volatile("" : "+v"(lane2));
;     const int r2 = lane2 & 31, h2 = lane2 >> 5;
;     const size_t obase = (size_t)(row0 + t0 + 4 * h2) * DM + hd * HD + r2, ybase = (size_t)(row0 + t0 + 4 * h2) * LDY + hd * HD + r2;
; #pragma unroll
;     for (int db = 0; db < 4; ++db) {
;         unsigned zv[16];
; #pragma unroll
;         for (int i = 0; i < 16; ++i) zv[i] = SZ_[obase + (size_t)(8 * (i >> 2) + (i & 3)) * DM + 32 * db];
; #pragma unroll
;         for (int i = 0; i < 16; ++i) asm volatile("" : "+v"(zv[i]));
; #pragma unroll
;         for (int i = 0; i < 16; ++i) {
;             const int q = 8 * (i >> 2) + 4 * h2 + (i & 3);
;             const bool ok = sample ? (q < NSQ) : (t0 + q < TP);
;             const float y = __uint_as_float(zv[i] << 16) * O[db][i];
;             if (ok) YS[ybase + (size_t)(8 * (i >> 2) + (i & 3)) * LDY + 32 * db] = (bf16_t)(pk2(y, y) & 0xffffu);
;         }
;     }
	v_lshlrev_b32_e32 v82, 16, v82
	v_lshlrev_b32_e32 v98, 16, v98
	v_lshlrev_b32_e32 v114, 16, v114
	v_lshlrev_b32_e32 v130, 16, v130
	v_mul_f32_e32 v82, v50, v82
	v_mul_f32_e32 v98, v34, v98
	v_mul_f32_e32 v114, v18, v114
	v_mul_f32_e32 v130, v2, v130
	v_cvt_pk_bf16_f32 v82, v82, v98
	v_cvt_pk_bf16_f32 v114, v114, v130
	global_store_short v70, v82, s[44:45]
	global_store_short_d16_hi v70, v82, s[44:45] offset:64
	global_store_short v70, v114, s[44:45] offset:128
	global_store_short_d16_hi v70, v114, s[44:45] offset:192
	s_add_u32 s44, s44, 0x1000
	s_addc_u32 s45, s45, 0
	s_waitcnt vmcnt(60)
	v_lshlrev_b32_e32 v83, 16, v83
	v_lshlrev_b32_e32 v99, 16, v99
	v_lshlrev_b32_e32 v115, 16, v115
	v_lshlrev_b32_e32 v131, 16, v131
	v_mul_f32_e32 v83, v51, v83
	v_mul_f32_e32 v99, v35, v99
	v_mul_f32_e32 v115, v19, v115
	v_mul_f32_e32 v131, v3, v131
	v_cvt_pk_bf16_f32 v83, v83, v99
	v_cvt_pk_bf16_f32 v115, v115, v131
	global_store_short v70, v83, s[44:45]
	global_store_short_d16_hi v70, v83, s[44:45] offset:64
	global_store_short v70, v115, s[44:45] offset:128
	global_store_short_d16_hi v70, v115, s[44:45] offset:192
	s_add_u32 s44, s44, 0x5000
	s_addc_u32 s45, s45, 0
	s_waitcnt vmcnt(60)
	v_lshlrev_b32_e32 v84, 16, v84
	v_lshlrev_b32_e32 v100, 16, v100
	v_lshlrev_b32_e32 v116, 16, v116
	v_lshlrev_b32_e32 v132, 16, v132
	v_mul_f32_e32 v84, v52, v84
	v_mul_f32_e32 v100, v36, v100
	v_mul_f32_e32 v116, v20, v116
	v_mul_f32_e32 v132, v4, v132
	v_cvt_pk_bf16_f32 v84, v84, v100
	v_cvt_pk_bf16_f32 v116, v116, v132
	global_store_short v70, v84, s[44:45]
	global_store_short_d16_hi v70, v84, s[44:45] offset:64
	global_store_short v70, v116, s[44:45] offset:128
	global_store_short_d16_hi v70, v116, s[44:45] offset:192
	s_add_u32 s44, s44, 0x1000
	s_addc_u32 s45, s45, 0
	s_waitcnt vmcnt(60)
	v_lshlrev_b32_e32 v85, 16, v85
	v_lshlrev_b32_e32 v101, 16, v101
	v_lshlrev_b32_e32 v117, 16, v117
	v_lshlrev_b32_e32 v133, 16, v133
	v_mul_f32_e32 v85, v53, v85
	v_mul_f32_e32 v101, v37, v101
	v_mul_f32_e32 v117, v21, v117
	v_mul_f32_e32 v133, v5, v133
	v_cvt_pk_bf16_f32 v85, v85, v101
	v_cvt_pk_bf16_f32 v117, v117, v133
	global_store_short v70, v85, s[44:45]
	global_store_short_d16_hi v70, v85, s[44:45] offset:64
	global_store_short v70, v117, s[44:45] offset:128
	global_store_short_d16_hi v70, v117, s[44:45] offset:192
	s_add_u32 s44, s44, 0x1000
	s_addc_u32 s45, s45, 0
	s_waitcnt vmcnt(60)
	v_lshlrev_b32_e32 v86, 16, v86
	v_lshlrev_b32_e32 v102, 16, v102
	v_lshlrev_b32_e32 v118, 16, v118
	v_lshlrev_b32_e32 v134, 16, v134
	v_mul_f32_e32 v86, v54, v86
	v_mul_f32_e32 v102, v38, v102
	v_mul_f32_e32 v118, v22, v118
	v_mul_f32_e32 v134, v6, v134
	v_cvt_pk_bf16_f32 v86, v86, v102
	v_cvt_pk_bf16_f32 v118, v118, v134
	global_store_short v70, v86, s[44:45]
	global_store_short_d16_hi v70, v86, s[44:45] offset:64
	global_store_short v70, v118, s[44:45] offset:128
	global_store_short_d16_hi v70, v118, s[44:45] offset:192
	s_add_u32 s44, s44, 0x1000
	s_addc_u32 s45, s45, 0
	s_waitcnt vmcnt(60)
	v_lshlrev_b32_e32 v87, 16, v87
	v_lshlrev_b32_e32 v103, 16, v103
	v_lshlrev_b32_e32 v119, 16, v119
	v_lshlrev_b32_e32 v135, 16, v135
	v_mul_f32_e32 v87, v55, v87
	v_mul_f32_e32 v103, v39, v103
	v_mul_f32_e32 v119, v23, v119
	v_mul_f32_e32 v135, v7, v135
	v_cvt_pk_bf16_f32 v87, v87, v103
	v_cvt_pk_bf16_f32 v119, v119, v135
	global_store_short v70, v87, s[44:45]
	global_store_short_d16_hi v70, v87, s[44:45] offset:64
	global_store_short v70, v119, s[44:45] offset:128
	global_store_short_d16_hi v70, v119, s[44:45] offset:192
	s_add_u32 s44, s44, 0x5000
	s_addc_u32 s45, s45, 0
	s_waitcnt vmcnt(60)
	v_lshlrev_b32_e32 v88, 16, v88
	v_lshlrev_b32_e32 v104, 16, v104
	v_lshlrev_b32_e32 v120, 16, v120
	v_lshlrev_b32_e32 v136, 16, v136
	v_mul_f32_e32 v88, v56, v88
	v_mul_f32_e32 v104, v40, v104
	v_mul_f32_e32 v120, v24, v120
	v_mul_f32_e32 v136, v8, v136
	v_cvt_pk_bf16_f32 v88, v88, v104
	v_cvt_pk_bf16_f32 v120, v120, v136
	global_store_short v70, v88, s[44:45]
	global_store_short_d16_hi v70, v88, s[44:45] offset:64
	global_store_short v70, v120, s[44:45] offset:128
	global_store_short_d16_hi v70, v120, s[44:45] offset:192
	s_add_u32 s44, s44, 0x1000
	s_addc_u32 s45, s45, 0
	s_waitcnt vmcnt(60)
; __device__ __forceinline__ unsigned pk2(float lo, float hi) { unsigned r; asm("v_cvt_pk_bf16_f32 %0, %1, %2" : "=v"(r) : "v"(lo), "v"(hi)); return r; }
; template <bool sample> __device__ __forceinline__ void attn_task(const Args& a, LAS unsigned char* vl, int lane, int task) {
;     ...
;     int lane2 = lane; asm volatile("" : "+v"(lane2));
;     const int r2 = lane2 & 31, h2 = lane2 >> 5;
;     const size_t obase = (size_t)(row0 + t0 + 4 * h2) * DM + hd * HD + r2, ybase = (size_t)(row0 + t0 + 4 * h2) * LDY + hd * HD + r2;
; #pragma unroll
;     for (int db = 0; db < 4; ++db) {
;         unsigned zv[16];
; #pragma unroll
;         for (int i = 0; i < 16; ++i) zv[i] = SZ_[obase + (size_t)(8 * (i >> 2) + (i & 3)) * DM + 32 * db];
; #pragma unroll
;         for (int i = 0; i < 16; ++i) asm volatile("" : "+v"(zv[i]));
; #pragma unroll
;         for (int i = 0; i < 16; ++i) {
;             const int q = 8 * (i >> 2) + 4 * h2 + (i & 3);
;             const bool ok = sample ? (q < NSQ) : (t0 + q < TP);
;             const float y = __uint_as_float(zv[i] << 16) * O[db][i];
;             if (ok) YS[ybase + (size_t)(8 * (i >> 2) + (i & 3)) * LDY + 32 * db] = (bf16_t)(pk2(y, y) & 0xffffu);
;         }
;     }
	v_lshlrev_b32_e32 v89, 16, v89
	v_lshlrev_b32_e32 v105, 16, v105
	v_lshlrev_b32_e32 v121, 16, v121
	v_lshlrev_b32_e32 v137, 16, v137
	v_mul_f32_e32 v89, v57, v89
	v_mul_f32_e32 v105, v41, v105
	v_mul_f32_e32 v121, v25, v121
	v_mul_f32_e32 v137, v9, v137
	v_cvt_pk_bf16_f32 v89, v89, v105
	v_cvt_pk_bf16_f32 v121, v121, v137
	global_store_short v70, v89, s[44:45]
	global_store_short_d16_hi v70, v89, s[44:45] offset:64
	global_store_short v70, v121, s[44:45] offset:128
	global_store_short_d16_hi v70, v121, s[44:45] offset:192
	s_add_u32 s44, s44, 0x1000
	s_addc_u32 s45, s45, 0
	s_waitcnt vmcnt(60)
	v_lshlrev_b32_e32 v90, 16, v90
	v_lshlrev_b32_e32 v106, 16, v106
	v_lshlrev_b32_e32 v122, 16, v122
	v_lshlrev_b32_e32 v138, 16, v138
	v_mul_f32_e32 v90, v58, v90
	v_mul_f32_e32 v106, v42, v106
	v_mul_f32_e32 v122, v26, v122
	v_mul_f32_e32 v138, v10, v138
	v_cvt_pk_bf16_f32 v90, v90, v106
	v_cvt_pk_bf16_f32 v122, v122, v138
	global_store_short v70, v90, s[44:45]
	global_store_short_d16_hi v70, v90, s[44:45] offset:64
	global_store_short v70, v122, s[44:45] offset:128
	global_store_short_d16_hi v70, v122, s[44:45] offset:192
	s_add_u32 s44, s44, 0x1000
	s_addc_u32 s45, s45, 0
	s_waitcnt vmcnt(60)
	v_lshlrev_b32_e32 v91, 16, v91
	v_lshlrev_b32_e32 v107, 16, v107
	v_lshlrev_b32_e32 v123, 16, v123
	v_lshlrev_b32_e32 v139, 16, v139
	v_mul_f32_e32 v91, v59, v91
	v_mul_f32_e32 v107, v43, v107
	v_mul_f32_e32 v123, v27, v123
	v_mul_f32_e32 v139, v11, v139
	v_cvt_pk_bf16_f32 v91, v91, v107
	v_cvt_pk_bf16_f32 v123, v123, v139
	global_store_short v70, v91, s[44:45]
	global_store_short_d16_hi v70, v91, s[44:45] offset:64
	global_store_short v70, v123, s[44:45] offset:128
	global_store_short_d16_hi v70, v123, s[44:45] offset:192
	s_add_u32 s44, s44, 0x5000
	s_addc_u32 s45, s45, 0
	s_waitcnt vmcnt(60)
	v_lshlrev_b32_e32 v92, 16, v92
	v_lshlrev_b32_e32 v108, 16, v108
	v_lshlrev_b32_e32 v124, 16, v124
	v_lshlrev_b32_e32 v140, 16, v140
	v_mul_f32_e32 v92, v60, v92
	v_mul_f32_e32 v108, v44, v108
	v_mul_f32_e32 v124, v28, v124
	v_mul_f32_e32 v140, v12, v140
	v_cvt_pk_bf16_f32 v92, v92, v108
	v_cvt_pk_bf16_f32 v124, v124, v140
	global_store_short v70, v92, s[44:45]
	global_store_short_d16_hi v70, v92, s[44:45] offset:64
	global_store_short v70, v124, s[44:45] offset:128
	global_store_short_d16_hi v70, v124, s[44:45] offset:192
	s_add_u32 s44, s44, 0x1000
	s_addc_u32 s45, s45, 0
	s_waitcnt vmcnt(60)
	v_lshlrev_b32_e32 v93, 16, v93
	v_lshlrev_b32_e32 v109, 16, v109
	v_lshlrev_b32_e32 v125, 16, v125
	v_lshlrev_b32_e32 v141, 16, v141
	v_mul_f32_e32 v93, v61, v93
	v_mul_f32_e32 v109, v45, v109
	v_mul_f32_e32 v125, v29, v125
	v_mul_f32_e32 v141, v13, v141
	v_cvt_pk_bf16_f32 v93, v93, v109
	v_cvt_pk_bf16_f32 v125, v125, v141
	global_store_short v70, v93, s[44:45]
	global_store_short_d16_hi v70, v93, s[44:45] offset:64
	global_store_short v70, v125, s[44:45] offset:128
	global_store_short_d16_hi v70, v125, s[44:45] offset:192
	s_add_u32 s44, s44, 0x1000
	s_addc_u32 s45, s45, 0
	s_waitcnt vmcnt(60)
	v_lshlrev_b32_e32 v94, 16, v94
	v_lshlrev_b32_e32 v110, 16, v110
	v_lshlrev_b32_e32 v126, 16, v126
	v_lshlrev_b32_e32 v142, 16, v142
	v_mul_f32_e32 v94, v62, v94
	v_mul_f32_e32 v110, v46, v110
	v_mul_f32_e32 v126, v30, v126
	v_mul_f32_e32 v142, v14, v142
	v_cvt_pk_bf16_f32 v94, v94, v110
	v_cvt_pk_bf16_f32 v126, v126, v142
	global_store_short v70, v94, s[44:45]
	global_store_short_d16_hi v70, v94, s[44:45] offset:64
	global_store_short v70, v126, s[44:45] offset:128
	global_store_short_d16_hi v70, v126, s[44:45] offset:192
	s_add_u32 s44, s44, 0x1000
	s_addc_u32 s45, s45, 0
	s_waitcnt vmcnt(60)
	v_lshlrev_b32_e32 v95, 16, v95
	v_lshlrev_b32_e32 v111, 16, v111
	v_lshlrev_b32_e32 v127, 16, v127
	v_lshlrev_b32_e32 v143, 16, v143
	v_mul_f32_e32 v95, v63, v95
	v_mul_f32_e32 v111, v47, v111
	v_mul_f32_e32 v127, v31, v127
	v_mul_f32_e32 v143, v15, v143
	v_cvt_pk_bf16_f32 v95, v95, v111
	v_cvt_pk_bf16_f32 v127, v127, v143
	global_store_short v70, v95, s[44:45]
	global_store_short_d16_hi v70, v95, s[44:45] offset:64
	global_store_short v70, v127, s[44:45] offset:128
	global_store_short_d16_hi v70, v127, s[44:45] offset:192
	s_branch .LBB0_55

; __global__ __launch_bounds__(512, 2) void fwd_mega(Args a0_) {
;     ...
;             if (wave == 0) { for (int task = nfull + blockIdx.x; task < NPT; task += G) attn_task<false>(a, vl, lane, task); }
.LBB0_189:
	s_cmp_lt_u32 s8, 128
	s_cbranch_scc0 .LBB0_326
	s_cmpk_lg_i32 s84, 0x100
	s_cbranch_scc1 .Lsb_orig
	v_readlane_b32 s0, v254, 35
	s_cmp_lg_u32 s0, 0
	s_cbranch_scc1 .Lsb_extra

; #define LAS __attribute__((address_space(3)))
; template <bool sample> __device__ __forceinline__ void attn_task(const Args& a, LAS unsigned char* vl, int lane, int task) {
;     const int r = lane & 31, h = lane >> 5;
;     const bf16_t* PA = (const bf16_t*)(a.ws + WS_PA);
;     const bf16_t *Pq = PA + 2 * (size_t)MPAD * DM, *KSW = (const bf16_t*)(a.ws + WS_KSW), *Pv = PA + 4 * (size_t)MPAD * DM, *SZ_ = PA + 5 * (size_t)MPAD * DM;
;     bf16_t* YS = (bf16_t*)(a.ws + WS_YC) + DM;
;     int seq, hd, g;
;     if (!sample) { seq = task / (NHEAD * NGRP); const int rem = task - seq * (NHEAD * NGRP); hd = rem / NGRP; g = rem - hd * NGRP; }
;     else { const int t2 = task - NPT; seq = t2 >> 3; hd = t2 & 7; g = 0; }
;     const int row0 = sample ? MP + seq * NSQ : seq * TP;
;     const int t0 = sample ? 0 : 32 * g;
;     const int qpos = (sample ? PAST : t0) + r;
;     const bool valid = sample ? (r < NSQ) : (t0 + r < TP);
;     const int kb_start = sample ? PAST / 32 : g;
;     bf16x8 qf[8];
;     {
;         const bf16_t* qp = Pq + (size_t)(row0 + t0 + r) * DM + hd * HD + 8 * h;
; #pragma unroll
;         for (int s = 0; s < 8; ++s) qf[s] = *(const bf16x8*)(qp + 16 * s);
;     }
;     f32x16 O[4];
; #pragma unroll
;     for (int db = 0; db < 4; ++db)
; #pragma unroll
;         for (int i = 0; i < 16; ++i) O[db][i] = 0.f;
;     float run = 0.f;
;     const int g4 = lane >> 4, i16 = lane & 15;
;     const unsigned troff = (unsigned)((4 * (g4 >> 1) + (i16 >> 2)) * VROW + (16 * (g4 & 1) + 4 * (i16 & 3)) * 2);
; __global__ __launch_bounds__(512, 2) void fwd_mega(Args a0_) {
;     ...
;             if (wave == 0) { for (int task = nfull + blockIdx.x; task < NPT; task += G) attn_task<false>(a, vl, lane, task); }
.Lsb_extra:
	s_waitcnt vmcnt(0)
	v_lshlrev_b32_e32 v2, 2, v186
	v_and_b32_e32 v3, 16, v216
	v_and_or_b32 v2, v2, 12, v3
	v_lshlrev_b32_e32 v7, 4, v216
	v_readlane_b32 s0, v252, 18
	v_lshlrev_b32_e32 v3, 1, v2
	v_lshrrev_b32_e32 v2, 3, v216
	v_bfe_u32 v4, v216, 2, 2
	v_lshrrev_b32_e32 v5, 1, v186
	v_and_b32_e32 v180, 48, v7
	v_readlane_b32 s1, v252, 19
	v_lshrrev_b32_e32 v1, 5, v186
	v_and_or_b32 v4, v2, 4, v4
	v_and_b32_e32 v6, 30, v5
	v_lshl_add_u64 v[188:189], s[0:1], 0, v[180:181]
	v_mov_b32_e32 v7, s20
	s_movk_i32 s0, 0x140
	v_or_b32_e32 v5, 1, v5
	v_lshlrev_b32_e32 v0, 3, v1
	v_lshlrev_b32_e32 v1, 2, v1
	v_mad_u32_u24 v4, v4, s0, v7
	v_mad_u32_u24 v8, v6, s0, v7
	v_mad_u32_u24 v5, v5, s0, v7
	v_readlane_b32 s0, v254, 44
	v_lshlrev_b32_e32 v2, 3, v186
	v_and_b32_e32 v208, 31, v216
	v_add_u32_e32 v209, s0, v1
	v_readlane_b32 s0, v254, 45
	v_cmp_gt_u32_e64 s[36:37], 32, v186
	v_lshlrev_b32_e32 v190, 1, v0
	v_add_u32_e32 v210, s0, v1
	v_add_u32_e32 v211, s0, v6
	v_lshlrev_b32_e32 v192, 1, v2
	v_add_u32_e32 v217, v8, v180
	v_add_u32_e32 v218, v5, v180
	v_add_u32_e32 v219, v4, v3
	v_readlane_b32 s8, v254, 39
	v_readlane_b32 s21, v254, 30
	s_cmpk_lg_i32 s84, 0x100
	s_cbranch_scc1 .Lsb_nodelta
	v_readlane_b32 s0, v254, 35
	s_cmp_eq_u32 s0, 0
	s_cbranch_scc1 .Lsb_nodelta
	v_readlane_b32 s0, v255, 15
	s_add_i32 s0, s0, 2
	s_mul_i32 s0, s0, s97
	s_add_i32 s0, s0, s72
	s_add_i32 s0, s0, 4
	s_sub_i32 s1, s0, s21
	s_mov_b32 s21, s0
	s_sub_i32 s8, s8, s1
	s_lshl_b32 s1, s1, 5
	v_add_u32_e32 v209, s1, v209
	v_add_u32_e32 v210, s1, v210
	v_add_u32_e32 v211, s1, v211

; __global__ __launch_bounds__(512, 2) void fwd_mega(Args a0_) {
;     ...
;             if (wave == 0) { for (int task = nfull + blockIdx.x; task < NPT; task += G) attn_task<false>(a, vl, lane, task); }
.LBB0_192:
	s_or_b64 exec, exec, s[0:1]
	s_add_i32 s21, s21, s84
	s_sub_i32 s8, s8, s84
	v_add_u32_e32 v209, s86, v209
	v_add_u32_e32 v210, s86, v210
	v_add_u32_e32 v211, s86, v211
	s_cmpk_lg_i32 s84, 0x100
	s_cbranch_scc1 .Lsb_be
	v_readlane_b32 s0, v254, 35
	s_cmp_lg_u32 s0, 0
	s_cbranch_scc1 .LBB0_325
.Lsb_be:
	s_cmpk_lt_i32 s21, 0x2020
	s_cbranch_scc0 .LBB0_325
